# diff loop row sums: 30 scalar v_add_f32 replaced by 15 v_pk_add_f32 on the v254:v255 accumulator pair (bit-identical order)
# baseline (speedup 1.0000x reference)
; #define ATT_SB() __builtin_amdgcn_sched_barrier(0)
; #define ATT_VRD(arr, ks) do { _Pragma("unroll") for (int cb = 0; cb < NCB; ++cb) { arr[cb][0] = vtr(vbp_ + voff[cb][0] + 4096 * (ks)); arr[cb][1] = vtr(vbp_ + voff[cb][1] + 4096 * (ks)); } } while (0)
; #define ATT_MM(arr, ks) do { _Pragma("unroll") for (int cb = 0; cb < NCB; ++cb) { const bf16x8 vf = {arr[cb][0][0], arr[cb][0][1], arr[cb][0][2], arr[cb][0][3], arr[cb][1][0], arr[cb][1][1], arr[cb][1][2], arr[cb][1][3]}; o[cb] = MFMA32(vf, pf[ks], o[cb]); } } while (0)
; template <bool FOX> ...
;     ...
;         ATT_MM(va, 0); ATT_VRD(va, 1); ATT_EXPCH(s0, 0, pf[0]); ATT_SB();
;         ATT_MM(va, 1); ATT_VRD(va, 2); ATT_EXPCH(s0, 8, pf[1]); ATT_SB();
;         ATT_MM(va, 2); ATT_VRD(va, 3); ATT_EXPCH(s1, 0, pf[2]); ATT_SB();
;         ATT_MM(va, 3); ATT_EXPCH(s1, 8, pf[3]); ATT_SB();
.LBB0_578:
	s_waitcnt lgkmcnt(0)
	v_mfma_f32_32x32x16_bf16 v[80:95], v[18:21], v[148:151], v[80:95]
	v_exp_f32_e32 v128, v128
	v_exp_f32_e32 v129, v129
	v_exp_f32_e32 v130, v130
	ds_read_b64_tr_b16 v[18:19], v17 offset:20480
	ds_read_b64_tr_b16 v[20:21], v31 offset:20480
	v_mfma_f32_32x32x16_bf16 v[64:79], v[22:25], v[148:151], v[64:79]
	v_exp_f32_e32 v131, v131
	v_exp_f32_e32 v132, v132
	v_pk_add_f32 v[254:255], v[128:129], v[130:131]
	ds_read_b64_tr_b16 v[22:23], v168 offset:20480
	ds_read_b64_tr_b16 v[24:25], v169 offset:20480
	v_mfma_f32_32x32x16_bf16 v[48:63], v[26:29], v[148:151], v[48:63]
	v_exp_f32_e32 v133, v133
	v_exp_f32_e32 v134, v134
	v_pk_add_f32 v[254:255], v[254:255], v[132:133]
	ds_read_b64_tr_b16 v[26:27], v170 offset:20480
	ds_read_b64_tr_b16 v[28:29], v171 offset:20480
	v_mfma_f32_32x32x16_bf16 v[32:47], v[164:167], v[148:151], v[32:47]
	v_exp_f32_e32 v135, v135
	ds_read_b64_tr_b16 v[164:165], v172 offset:20480
	ds_read_b64_tr_b16 v[166:167], v173 offset:20480
	v_pk_add_f32 v[254:255], v[254:255], v[134:135]
	v_cvt_pk_bf16_f32 v148, v128, v129
	v_cvt_pk_bf16_f32 v149, v130, v131
	v_cvt_pk_bf16_f32 v150, v132, v133
	v_cvt_pk_bf16_f32 v151, v134, v135
	s_waitcnt lgkmcnt(0)
	v_mfma_f32_32x32x16_bf16 v[80:95], v[18:21], v[152:155], v[80:95]
	v_exp_f32_e32 v136, v136
	v_exp_f32_e32 v137, v137
	v_exp_f32_e32 v138, v138
	ds_read_b64_tr_b16 v[18:19], v17 offset:24576
	ds_read_b64_tr_b16 v[20:21], v31 offset:24576
	v_mfma_f32_32x32x16_bf16 v[64:79], v[22:25], v[152:155], v[64:79]
	v_exp_f32_e32 v139, v139
	v_exp_f32_e32 v140, v140
	v_pk_add_f32 v[254:255], v[254:255], v[136:137]
	ds_read_b64_tr_b16 v[22:23], v168 offset:24576
	ds_read_b64_tr_b16 v[24:25], v169 offset:24576
	v_mfma_f32_32x32x16_bf16 v[48:63], v[26:29], v[152:155], v[48:63]
	v_exp_f32_e32 v141, v141
	v_exp_f32_e32 v142, v142
	v_pk_add_f32 v[254:255], v[254:255], v[138:139]
	ds_read_b64_tr_b16 v[26:27], v170 offset:24576
	ds_read_b64_tr_b16 v[28:29], v171 offset:24576
	v_mfma_f32_32x32x16_bf16 v[32:47], v[164:167], v[152:155], v[32:47]
	v_exp_f32_e32 v143, v143
	v_pk_add_f32 v[254:255], v[254:255], v[140:141]
	ds_read_b64_tr_b16 v[164:165], v172 offset:24576
	ds_read_b64_tr_b16 v[166:167], v173 offset:24576
	v_pk_add_f32 v[254:255], v[254:255], v[142:143]
	v_cvt_pk_bf16_f32 v152, v136, v137
	v_cvt_pk_bf16_f32 v153, v138, v139
	v_cvt_pk_bf16_f32 v154, v140, v141
	v_cvt_pk_bf16_f32 v155, v142, v143
	s_waitcnt lgkmcnt(0)
	v_mfma_f32_32x32x16_bf16 v[80:95], v[18:21], v[160:163], v[80:95]
	v_exp_f32_e32 v112, v112
	v_exp_f32_e32 v113, v113
	v_exp_f32_e32 v114, v114
	ds_read_b64_tr_b16 v[18:19], v17 offset:28672
	ds_read_b64_tr_b16 v[20:21], v31 offset:28672
	v_mfma_f32_32x32x16_bf16 v[64:79], v[22:25], v[160:163], v[64:79]
	v_exp_f32_e32 v115, v115
	v_exp_f32_e32 v116, v116
	v_pk_add_f32 v[254:255], v[254:255], v[112:113]
	ds_read_b64_tr_b16 v[22:23], v168 offset:28672
	ds_read_b64_tr_b16 v[24:25], v169 offset:28672
	v_mfma_f32_32x32x16_bf16 v[48:63], v[26:29], v[160:163], v[48:63]
	v_exp_f32_e32 v117, v117
	v_exp_f32_e32 v118, v118
	v_pk_add_f32 v[254:255], v[254:255], v[114:115]
	ds_read_b64_tr_b16 v[26:27], v170 offset:28672
	ds_read_b64_tr_b16 v[28:29], v171 offset:28672
	v_mfma_f32_32x32x16_bf16 v[32:47], v[164:167], v[160:163], v[32:47]
	v_exp_f32_e32 v119, v119
	v_pk_add_f32 v[254:255], v[254:255], v[116:117]
	ds_read_b64_tr_b16 v[164:165], v172 offset:28672
	ds_read_b64_tr_b16 v[166:167], v173 offset:28672
	v_pk_add_f32 v[254:255], v[254:255], v[118:119]
	v_cvt_pk_bf16_f32 v160, v112, v113
	v_cvt_pk_bf16_f32 v161, v114, v115
	v_cvt_pk_bf16_f32 v162, v116, v117
	v_cvt_pk_bf16_f32 v163, v118, v119
	s_waitcnt lgkmcnt(0)
	s_and_b64 vcc, exec, s[10:11]
	s_cbranch_vccnz .Ldiff_bar0
	s_waitcnt vmcnt(4)
	s_barrier
	s_branch .Ldiff_st3

; #define ATT_SB() __builtin_amdgcn_sched_barrier(0)
; #define ATT_MM(arr, ks) do { _Pragma("unroll") for (int cb = 0; cb < NCB; ++cb) { const bf16x8 vf = {arr[cb][0][0], arr[cb][0][1], arr[cb][0][2], arr[cb][0][3], arr[cb][1][0], arr[cb][1][1], arr[cb][1][2], arr[cb][1][3]}; o[cb] = MFMA32(vf, pf[ks], o[cb]); } } while (0)
; template <bool FOX> ...
;     ...
;         ATT_MM(va, 3); ATT_EXPCH(s1, 8, pf[3]); ATT_SB();
;         lsum += ps2.x + ps2.y;
.Ldiff_st3:
	v_mfma_f32_32x32x16_bf16 v[80:95], v[18:21], v[156:159], v[80:95]
	v_exp_f32_e32 v120, v120
	v_exp_f32_e32 v121, v121
	v_exp_f32_e32 v122, v122
	v_mfma_f32_32x32x16_bf16 v[64:79], v[22:25], v[156:159], v[64:79]
	v_exp_f32_e32 v123, v123
	v_exp_f32_e32 v124, v124
	v_pk_add_f32 v[254:255], v[254:255], v[120:121]
	v_mfma_f32_32x32x16_bf16 v[48:63], v[26:29], v[156:159], v[48:63]
	v_exp_f32_e32 v125, v125
	v_exp_f32_e32 v126, v126
	v_pk_add_f32 v[254:255], v[254:255], v[122:123]
	v_mfma_f32_32x32x16_bf16 v[32:47], v[164:167], v[156:159], v[32:47]
	v_exp_f32_e32 v127, v127
	v_pk_add_f32 v[254:255], v[254:255], v[124:125]
	v_pk_add_f32 v[254:255], v[254:255], v[126:127]
	v_cvt_pk_bf16_f32 v156, v120, v121
	v_cvt_pk_bf16_f32 v157, v122, v123
	v_cvt_pk_bf16_f32 v158, v124, v125
	v_cvt_pk_bf16_f32 v159, v126, v127
	s_andn2_b64 vcc, exec, s[6:7]
	s_cbranch_vccz .LBB0_584
